# lru_gate conv stage: PROJ tap rows prefetched for all four taps at item start
# speedup vs baseline: 1.0001x; 1.0001x over previous
; DI float bflo(unsigned w) { return __uint_as_float(w << 16); }
; DI float bfhi(unsigned w) { return __uint_as_float(w & 0xffff0000u); }
; DI void lru_gate_phase(const Ctx& C, const bf16* PROJ, const float* conv_w, const float* conv_b, const bf16* LW, const float* gate_b, const float* lam, bf16* LA, bf16* BV) {
;     ...
;             const int r = tid >> 3, cs = tid & 7, c0 = h * 128 + cs * 16, tok = tok0 + r, ts = tok & (SEQ - 1);
;             float a[16];
; #pragma unroll
;             for (int i = 0; i < 16; ++i) a[i] = conv_b[c0 + i];
; #pragma unroll
;             for (int k = 0; k < 4; ++k) { const int tk = ts + k - 2;
;                 if (tk >= 0 && tk < SEQ) { const v4u* p = (const v4u*)(PROJ + (size_t)(tok + k - 2) * AB_N + c0); const v4u x0 = p[0], x1 = p[1]; const float* wk = conv_w + k * 1024 + c0;
;                     a[0] += wk[0] * bflo(x0.x); a[1] += wk[1] * bfhi(x0.x); a[2] += wk[2] * bflo(x0.y); a[3] += wk[3] * bfhi(x0.y); a[4] += wk[4] * bflo(x0.z); a[5] += wk[5] * bfhi(x0.z); a[6] += wk[6] * bflo(x0.w); a[7] += wk[7] * bfhi(x0.w);
;                     a[8] += wk[8] * bflo(x1.x); a[9] += wk[9] * bfhi(x1.x); a[10] += wk[10] * bflo(x1.y); a[11] += wk[11] * bfhi(x1.y); a[12] += wk[12] * bflo(x1.z); a[13] += wk[13] * bfhi(x1.z); a[14] += wk[14] * bflo(x1.w); a[15] += wk[15] * bfhi(x1.w); } }
.LBB0_1197:
	s_lshl_b32 s8, s14, 7
	s_and_b32 s92, s8, 0x380
	v_or_b32_e32 v22, s92, v1
	v_readlane_b32 s40, v252, 61
	v_lshlrev_b32_e32 v2, 2, v22
	v_readlane_b32 s44, v255, 1
	v_readlane_b32 s45, v255, 2
	s_nop 4
	global_load_dwordx4 v[6:9], v2, s[44:45] offset:48
	global_load_dwordx4 v[10:13], v2, s[44:45] offset:32
	global_load_dwordx4 v[14:17], v2, s[44:45] offset:16
	global_load_dwordx4 v[18:21], v2, s[44:45]
	s_lshl_b32 s8, s14, 3
	s_andn2_b32 s8, s8, 63
	v_add_u32_e32 v26, s8, v0
	v_readlane_b32 s42, v252, 63
	v_readlane_b32 s43, v255, 0
	v_and_b32_e32 v27, 0x1fff, v26
	v_lshlrev_b32_e32 v22, 1, v22
	v_mov_b32_e32 v23, v3
	v_lshl_add_u64 v[24:25], s[86:87], 0, v[22:23]
	v_lshl_add_u64 v[22:23], s[42:43], 0, v[2:3]
	v_add_u32_e32 v202, -2, v26
	v_mul_lo_u32 v202, v202, s63
	v_ashrrev_i32_e32 v203, 31, v202
	v_lshl_add_u64 v[200:201], v[24:25], 0, v[202:203]
	global_load_dwordx4 v[168:171], v[200:201], off
	global_load_dwordx4 v[172:175], v[200:201], off offset:16
	v_add_u32_e32 v202, -1, v26
	v_mul_lo_u32 v202, v202, s63
	v_ashrrev_i32_e32 v203, 31, v202
	v_lshl_add_u64 v[200:201], v[24:25], 0, v[202:203]
	global_load_dwordx4 v[176:179], v[200:201], off
	global_load_dwordx4 v[180:183], v[200:201], off offset:16
	v_mul_lo_u32 v202, v26, s63
	v_ashrrev_i32_e32 v203, 31, v202
	v_lshl_add_u64 v[200:201], v[24:25], 0, v[202:203]
	global_load_dwordx4 v[184:187], v[200:201], off
	global_load_dwordx4 v[188:191], v[200:201], off offset:16
	v_add_u32_e32 v202, 1, v26
	v_mul_lo_u32 v202, v202, s63
	v_ashrrev_i32_e32 v203, 31, v202
	v_lshl_add_u64 v[200:201], v[24:25], 0, v[202:203]
	global_load_dwordx4 v[192:195], v[200:201], off
	global_load_dwordx4 v[196:199], v[200:201], off offset:16
	v_cmp_lt_u32_e32 vcc, 1, v27
	v_readlane_b32 s41, v252, 62
	v_readlane_b32 s46, v255, 3
	v_readlane_b32 s47, v255, 4
	v_readlane_b32 s48, v255, 5
	v_readlane_b32 s49, v255, 6
	v_readlane_b32 s50, v255, 7
	v_readlane_b32 s51, v255, 8
	v_readlane_b32 s52, v255, 9
	v_readlane_b32 s53, v255, 10
	v_readlane_b32 s54, v255, 11
	v_readlane_b32 s55, v255, 12
	s_and_saveexec_b64 s[8:9], vcc
	s_cbranch_execz .LBB0_1199
	v_add_u32_e32 v2, -2, v26
	s_nop 0
	global_load_dwordx4 v[36:39], v[22:23], off offset:48
	global_load_dwordx4 v[40:43], v[22:23], off offset:32
	global_load_dwordx4 v[44:47], v[22:23], off offset:16
	global_load_dwordx4 v[48:51], v[22:23], off
	s_waitcnt vmcnt(0) lgkmcnt(0)
	v_lshlrev_b32_e32 v52, 16, v168
	v_and_b32_e32 v53, 0xffff0000, v168
	v_lshlrev_b32_e32 v28, 16, v169
	v_and_b32_e32 v29, 0xffff0000, v169
	v_pk_fma_f32 v[20:21], v[50:51], v[28:29], v[20:21]
	v_lshlrev_b32_e32 v28, 16, v170
	v_and_b32_e32 v29, 0xffff0000, v170
	v_pk_fma_f32 v[14:15], v[44:45], v[28:29], v[14:15]
	v_lshlrev_b32_e32 v28, 16, v171
	v_and_b32_e32 v29, 0xffff0000, v171
	v_pk_fma_f32 v[16:17], v[46:47], v[28:29], v[16:17]
	v_lshlrev_b32_e32 v28, 16, v172
	v_and_b32_e32 v29, 0xffff0000, v172
	v_pk_fma_f32 v[10:11], v[40:41], v[28:29], v[10:11]
	v_lshlrev_b32_e32 v28, 16, v173
	v_and_b32_e32 v29, 0xffff0000, v173
	v_pk_fma_f32 v[12:13], v[42:43], v[28:29], v[12:13]
	v_lshlrev_b32_e32 v28, 16, v174
	v_and_b32_e32 v29, 0xffff0000, v174
	v_pk_fma_f32 v[6:7], v[36:37], v[28:29], v[6:7]
	v_lshlrev_b32_e32 v28, 16, v175
	v_and_b32_e32 v29, 0xffff0000, v175
	v_pk_fma_f32 v[18:19], v[48:49], v[52:53], v[18:19]
	v_pk_fma_f32 v[8:9], v[38:39], v[28:29], v[8:9]
; DI float bflo(unsigned w) { return __uint_as_float(w << 16); }
; DI float bfhi(unsigned w) { return __uint_as_float(w & 0xffff0000u); }
; DI void lru_gate_phase(const Ctx& C, const bf16* PROJ, const float* conv_w, const float* conv_b, const bf16* LW, const float* gate_b, const float* lam, bf16* LA, bf16* BV) {
;     ...
;             for (int k = 0; k < 4; ++k) { const int tk = ts + k - 2;
;                 if (tk >= 0 && tk < SEQ) { const v4u* p = (const v4u*)(PROJ + (size_t)(tok + k - 2) * AB_N + c0); const v4u x0 = p[0], x1 = p[1]; const float* wk = conv_w + k * 1024 + c0;
;                     a[0] += wk[0] * bflo(x0.x); a[1] += wk[1] * bfhi(x0.x); a[2] += wk[2] * bflo(x0.y); a[3] += wk[3] * bfhi(x0.y); a[4] += wk[4] * bflo(x0.z); a[5] += wk[5] * bfhi(x0.z); a[6] += wk[6] * bflo(x0.w); a[7] += wk[7] * bfhi(x0.w);
;                     a[8] += wk[8] * bflo(x1.x); a[9] += wk[9] * bfhi(x1.x); a[10] += wk[10] * bflo(x1.y); a[11] += wk[11] * bfhi(x1.y); a[12] += wk[12] * bflo(x1.z); a[13] += wk[13] * bfhi(x1.z); a[14] += wk[14] * bflo(x1.w); a[15] += wk[15] * bfhi(x1.w); } }
.LBB0_1199:
	s_or_b64 exec, exec, s[8:9]
	v_cmp_ne_u32_e32 vcc, 0, v27
	s_and_saveexec_b64 s[8:9], vcc
	s_cbranch_execz .LBB0_1201
	v_add_u32_e32 v2, -1, v26
	s_mov_b64 s[10:11], 0x1000
	v_add_co_u32_e32 v36, vcc, 0x1000, v22
	v_lshl_add_u64 v[48:49], v[22:23], 0, s[10:11]
	v_addc_co_u32_e32 v37, vcc, 0, v23, vcc
	global_load_dwordx4 v[36:39], v[36:37], off
	s_nop 0
	global_load_dwordx4 v[40:43], v[48:49], off offset:48
	global_load_dwordx4 v[44:47], v[48:49], off offset:32
	s_nop 0
	global_load_dwordx4 v[48:51], v[48:49], off offset:16
	s_waitcnt vmcnt(0) lgkmcnt(0)
	v_lshlrev_b32_e32 v52, 16, v176
	v_and_b32_e32 v53, 0xffff0000, v176
	v_lshlrev_b32_e32 v28, 16, v177
	v_and_b32_e32 v29, 0xffff0000, v177
	v_pk_fma_f32 v[20:21], v[38:39], v[28:29], v[20:21]
	v_lshlrev_b32_e32 v28, 16, v178
	v_and_b32_e32 v29, 0xffff0000, v178
	v_pk_fma_f32 v[14:15], v[48:49], v[28:29], v[14:15]
	v_lshlrev_b32_e32 v28, 16, v179
	v_and_b32_e32 v29, 0xffff0000, v179
	v_pk_fma_f32 v[16:17], v[50:51], v[28:29], v[16:17]
	v_lshlrev_b32_e32 v28, 16, v180
	v_and_b32_e32 v29, 0xffff0000, v180
	v_pk_fma_f32 v[10:11], v[44:45], v[28:29], v[10:11]
	v_lshlrev_b32_e32 v28, 16, v181
	v_and_b32_e32 v29, 0xffff0000, v181
	v_pk_fma_f32 v[12:13], v[46:47], v[28:29], v[12:13]
	v_lshlrev_b32_e32 v28, 16, v182
	v_and_b32_e32 v29, 0xffff0000, v182
	v_pk_fma_f32 v[6:7], v[40:41], v[28:29], v[6:7]
	v_lshlrev_b32_e32 v28, 16, v183
	v_and_b32_e32 v29, 0xffff0000, v183
	v_pk_fma_f32 v[18:19], v[36:37], v[52:53], v[18:19]
	v_pk_fma_f32 v[8:9], v[42:43], v[28:29], v[8:9]
.LBB0_1201:
	s_or_b64 exec, exec, s[8:9]
	v_add_co_u32_e32 v36, vcc, 0x2000, v22
	v_lshl_add_u64 v[48:49], v[22:23], 0, s[80:81]
	v_addc_co_u32_e32 v37, vcc, 0, v23, vcc
	global_load_dwordx4 v[36:39], v[36:37], off
	s_nop 0
	global_load_dwordx4 v[40:43], v[48:49], off offset:48
	global_load_dwordx4 v[44:47], v[48:49], off offset:32
	s_nop 0
	global_load_dwordx4 v[48:51], v[48:49], off offset:16
	v_cmp_ne_u32_e32 vcc, s18, v27
	s_waitcnt vmcnt(0) lgkmcnt(0)
	v_lshlrev_b32_e32 v52, 16, v184
	v_and_b32_e32 v53, 0xffff0000, v184
	v_lshlrev_b32_e32 v28, 16, v185
	v_and_b32_e32 v29, 0xffff0000, v185
	v_pk_fma_f32 v[20:21], v[38:39], v[28:29], v[20:21]
	v_lshlrev_b32_e32 v28, 16, v186
	v_and_b32_e32 v29, 0xffff0000, v186
	v_pk_fma_f32 v[14:15], v[48:49], v[28:29], v[14:15]
	v_lshlrev_b32_e32 v28, 16, v187
	v_and_b32_e32 v29, 0xffff0000, v187
	v_pk_fma_f32 v[16:17], v[50:51], v[28:29], v[16:17]
	v_lshlrev_b32_e32 v28, 16, v188
	v_and_b32_e32 v29, 0xffff0000, v188
	v_pk_fma_f32 v[10:11], v[44:45], v[28:29], v[10:11]
	v_lshlrev_b32_e32 v28, 16, v189
	v_and_b32_e32 v29, 0xffff0000, v189
	v_pk_fma_f32 v[12:13], v[46:47], v[28:29], v[12:13]
	v_lshlrev_b32_e32 v28, 16, v190
	v_and_b32_e32 v29, 0xffff0000, v190
	v_pk_fma_f32 v[6:7], v[40:41], v[28:29], v[6:7]
	v_lshlrev_b32_e32 v28, 16, v191
	v_and_b32_e32 v29, 0xffff0000, v191
	v_pk_fma_f32 v[18:19], v[36:37], v[52:53], v[18:19]
	v_pk_fma_f32 v[8:9], v[42:43], v[28:29], v[8:9]
	s_and_saveexec_b64 s[8:9], vcc
	s_cbranch_execz .LBB0_1203
	v_add_u32_e32 v2, 1, v26
	s_mov_b64 s[10:11], 0x3000
	v_lshl_add_u64 v[44:45], v[22:23], 0, s[10:11]
	v_add_co_u32_e32 v22, vcc, 0x3000, v22
	s_nop 1
	v_addc_co_u32_e32 v23, vcc, 0, v23, vcc
	global_load_dwordx4 v[32:35], v[22:23], off
	global_load_dwordx4 v[36:39], v[44:45], off offset:48
	global_load_dwordx4 v[40:43], v[44:45], off offset:32
	s_nop 0
	global_load_dwordx4 v[44:47], v[44:45], off offset:16
	s_waitcnt vmcnt(0) lgkmcnt(0)
	v_lshlrev_b32_e32 v22, 16, v192
	v_and_b32_e32 v23, 0xffff0000, v192
	v_pk_fma_f32 v[18:19], v[32:33], v[22:23], v[18:19]
	v_lshlrev_b32_e32 v22, 16, v193
	v_and_b32_e32 v23, 0xffff0000, v193
	v_pk_fma_f32 v[20:21], v[34:35], v[22:23], v[20:21]
	v_lshlrev_b32_e32 v22, 16, v194
	v_and_b32_e32 v23, 0xffff0000, v194
	v_pk_fma_f32 v[14:15], v[44:45], v[22:23], v[14:15]
	v_lshlrev_b32_e32 v22, 16, v195
	v_and_b32_e32 v23, 0xffff0000, v195
	v_pk_fma_f32 v[16:17], v[46:47], v[22:23], v[16:17]
	v_lshlrev_b32_e32 v22, 16, v196
	v_and_b32_e32 v23, 0xffff0000, v196
	v_pk_fma_f32 v[10:11], v[40:41], v[22:23], v[10:11]
	v_lshlrev_b32_e32 v22, 16, v197
	v_and_b32_e32 v23, 0xffff0000, v197
	v_pk_fma_f32 v[12:13], v[42:43], v[22:23], v[12:13]
	v_lshlrev_b32_e32 v22, 16, v198
	v_and_b32_e32 v23, 0xffff0000, v198
	v_pk_fma_f32 v[6:7], v[36:37], v[22:23], v[6:7]
	v_lshlrev_b32_e32 v22, 16, v199
	v_and_b32_e32 v23, 0xffff0000, v199
	v_pk_fma_f32 v[8:9], v[38:39], v[22:23], v[8:9]
